# tgain: P0 weight-transpose gains loaded once per item (v102..v109) instead of once per 8-row group, later waits LDS-only; on top of v65
# speedup vs baseline: 1.0013x; 1.0013x over previous
; template <bool MAPIN>
; __device__ __forceinline__ void transpose_item(const float* W, int K, int N, bf16_t* WT, LAS float* scr, int item, int lane, const float* gk = nullptr) {
;     const int nblk = N / 32, kb = item / nblk, nb = item % nblk, k0 = 64 * kb, n0 = 32 * nb;
; #pragma unroll 8
;     for (int i = 0; i < 32; ++i) { const int kk = 2 * i + (lane >> 5); scr[kk * 33 + (lane & 31)] = W[(size_t)(k0 + kk) * N + n0 + (lane & 31)]; }
.LBB0_108:
	s_lshl_b32 s19, s16, 1
	s_lshl_b32 s20, s17, 1
	v_or_b32_e32 v14, s20, v4
	s_add_i32 s22, s19, 4
	s_add_i32 s23, s20, 4
	v_mov_b32_e32 v9, v15
	s_add_i32 s25, s20, 8
	v_lshlrev_b64 v[48:49], 13, v[14:15]
	v_or_b32_e32 v8, s22, v5
	v_or_b32_e32 v14, s23, v4
	v_mov_b32_e32 v7, v15
	v_or_b32_e32 v6, s19, v5
	s_add_i32 s27, s20, 12
	v_lshlrev_b64 v[8:9], 13, v[8:9]
	v_lshlrev_b64 v[50:51], 13, v[14:15]
	v_or_b32_e32 v14, s25, v4
	s_add_i32 s24, s19, 8
	s_add_i32 s26, s19, 12
	s_add_i32 s29, s20, 16
	v_lshlrev_b64 v[6:7], 13, v[6:7]
	v_lshl_add_u64 v[48:49], v[2:3], 0, v[48:49]
	v_lshl_add_u64 v[8:9], v[2:3], 0, v[8:9]
	v_lshlrev_b64 v[52:53], 13, v[14:15]
	v_or_b32_e32 v14, s27, v4
	v_mov_b32_e32 v23, v15
	v_mov_b32_e32 v39, v15
	s_add_i32 s31, s20, 20
	v_or_b32_e32 v22, s24, v5
	v_or_b32_e32 v38, s26, v5
	v_lshl_add_u64 v[6:7], v[2:3], 0, v[6:7]
	v_lshl_add_u64 v[50:51], v[2:3], 0, v[50:51]
	global_load_dword v21, v[48:49], off
	global_load_dword v25, v[6:7], off
	global_load_dword v65, v[50:51], off
	global_load_dword v67, v[8:9], off
	v_lshlrev_b64 v[8:9], 13, v[14:15]
	v_or_b32_e32 v14, s29, v4
	s_add_i32 s28, s19, 16
	s_add_i32 s30, s19, 20
	s_add_i32 s35, s20, 24
	v_lshlrev_b64 v[22:23], 13, v[22:23]
	v_lshlrev_b64 v[38:39], 13, v[38:39]
	v_lshl_add_u64 v[6:7], v[2:3], 0, v[52:53]
	v_lshl_add_u64 v[8:9], v[2:3], 0, v[8:9]
	v_lshlrev_b64 v[48:49], 13, v[14:15]
	v_or_b32_e32 v14, s31, v4
	v_mov_b32_e32 v41, v15
	v_mov_b32_e32 v43, v15
	s_add_i32 s34, s19, 24
	s_add_i32 s76, s19, 28
	s_add_i32 s77, s20, 28
	v_or_b32_e32 v40, s28, v5
	v_or_b32_e32 v42, s30, v5
	v_lshl_add_u64 v[22:23], v[2:3], 0, v[22:23]
	v_lshl_add_u64 v[38:39], v[2:3], 0, v[38:39]
	global_load_dword v68, v[6:7], off
	global_load_dword v69, v[22:23], off
	global_load_dword v70, v[8:9], off
	global_load_dword v71, v[38:39], off
	v_lshlrev_b64 v[8:9], 13, v[14:15]
	v_or_b32_e32 v14, s35, v4
	v_mov_b32_e32 v45, v15
	v_mov_b32_e32 v47, v15
	v_or_b32_e32 v44, s34, v5
	v_or_b32_e32 v46, s76, v5
	v_lshlrev_b64 v[40:41], 13, v[40:41]
	v_lshlrev_b64 v[42:43], 13, v[42:43]
	v_lshl_add_u64 v[6:7], v[2:3], 0, v[48:49]
	v_lshl_add_u64 v[8:9], v[2:3], 0, v[8:9]
	v_lshlrev_b64 v[22:23], 13, v[14:15]
	v_or_b32_e32 v14, s77, v4
	v_lshlrev_b64 v[44:45], 13, v[44:45]
	v_lshlrev_b64 v[46:47], 13, v[46:47]
	v_lshl_add_u64 v[40:41], v[2:3], 0, v[40:41]
	v_lshl_add_u64 v[42:43], v[2:3], 0, v[42:43]
	global_load_dword v72, v[6:7], off
	global_load_dword v73, v[40:41], off
	global_load_dword v74, v[8:9], off
	global_load_dword v75, v[42:43], off
	v_lshl_add_u64 v[6:7], v[2:3], 0, v[22:23]
	v_lshlrev_b64 v[8:9], 13, v[14:15]
	v_lshl_add_u64 v[44:45], v[2:3], 0, v[44:45]
	v_lshl_add_u64 v[46:47], v[2:3], 0, v[46:47]
	v_lshl_add_u64 v[8:9], v[2:3], 0, v[8:9]
	global_load_dword v14, v[6:7], off
	global_load_dword v76, v[44:45], off
	global_load_dword v77, v[8:9], off
	global_load_dword v78, v[46:47], off
	v_or_b32_e32 v8, s19, v13
	v_or_b32_e32 v6, s20, v12
	s_add_i32 s17, s17, 16
	s_add_i32 s16, s16, 16
	s_add_i32 s18, s18, -16
	v_mad_u64_u32 v[6:7], s[20:21], v6, s36, v[16:17]
	v_mad_u64_u32 v[8:9], s[20:21], v8, s36, v[16:17]
	v_or_b32_e32 v7, s22, v13
	v_or_b32_e32 v9, s23, v12
	v_or_b32_e32 v42, s24, v13
	v_or_b32_e32 v40, s25, v12
	v_or_b32_e32 v46, s26, v13
	v_or_b32_e32 v44, s27, v12
	v_or_b32_e32 v50, s28, v13
	v_or_b32_e32 v48, s29, v12
	v_or_b32_e32 v54, s30, v13
	v_or_b32_e32 v52, s31, v12
	v_or_b32_e32 v58, s34, v13
	v_or_b32_e32 v56, s35, v12
	v_or_b32_e32 v62, s76, v13
	v_or_b32_e32 v60, s77, v12
	s_cmp_lg_u32 s18, 0
	v_mad_u64_u32 v[22:23], s[20:21], v9, s36, v[16:17]
	v_mad_u64_u32 v[38:39], s[20:21], v7, s36, v[16:17]
	v_mad_u64_u32 v[40:41], s[20:21], v40, s36, v[16:17]
	v_mad_u64_u32 v[42:43], s[20:21], v42, s36, v[16:17]
	v_mad_u64_u32 v[44:45], s[20:21], v44, s36, v[16:17]
	v_mad_u64_u32 v[46:47], s[20:21], v46, s36, v[16:17]
	v_mad_u64_u32 v[48:49], s[20:21], v48, s36, v[16:17]
	v_mad_u64_u32 v[50:51], s[20:21], v50, s36, v[16:17]
	v_mad_u64_u32 v[52:53], s[20:21], v52, s36, v[16:17]
	v_mad_u64_u32 v[54:55], s[20:21], v54, s36, v[16:17]
	v_mad_u64_u32 v[56:57], s[20:21], v56, s36, v[16:17]
	v_mad_u64_u32 v[58:59], s[20:21], v58, s36, v[16:17]
	v_mad_u64_u32 v[60:61], s[20:21], v60, s36, v[16:17]
	v_mad_u64_u32 v[62:63], s[20:21], v62, s36, v[16:17]
	v_mov_b32_e32 v145, v15
	s_lshl_b32 s19, s16, 1
	s_lshl_b32 s20, s17, 1
	v_or_b32_e32 v144, s20, v4
	s_add_i32 s22, s19, 4
	s_add_i32 s23, s20, 4
	v_mov_b32_e32 v139, v145
	s_add_i32 s25, s20, 8
	v_lshlrev_b64 v[178:179], 13, v[144:145]
	v_or_b32_e32 v138, s22, v5
	v_or_b32_e32 v144, s23, v4
	v_mov_b32_e32 v137, v145
	v_or_b32_e32 v136, s19, v5
	s_add_i32 s27, s20, 12
	v_lshlrev_b64 v[138:139], 13, v[138:139]
	v_lshlrev_b64 v[180:181], 13, v[144:145]
	v_or_b32_e32 v144, s25, v4
	s_add_i32 s24, s19, 8
	s_add_i32 s26, s19, 12
	s_add_i32 s29, s20, 16
	v_lshlrev_b64 v[136:137], 13, v[136:137]
	v_lshl_add_u64 v[178:179], v[2:3], 0, v[178:179]
	v_lshl_add_u64 v[138:139], v[2:3], 0, v[138:139]
	v_lshlrev_b64 v[182:183], 13, v[144:145]
	v_or_b32_e32 v144, s27, v4
	v_mov_b32_e32 v153, v145
	v_mov_b32_e32 v169, v145
	s_add_i32 s31, s20, 20
	v_or_b32_e32 v152, s24, v5
	v_or_b32_e32 v168, s26, v5
	v_lshl_add_u64 v[136:137], v[2:3], 0, v[136:137]
	v_lshl_add_u64 v[180:181], v[2:3], 0, v[180:181]
	global_load_dword v151, v[178:179], off
	global_load_dword v155, v[136:137], off
	global_load_dword v195, v[180:181], off
	global_load_dword v197, v[138:139], off
	v_lshlrev_b64 v[138:139], 13, v[144:145]
	v_or_b32_e32 v144, s29, v4
	s_add_i32 s28, s19, 16
	s_add_i32 s30, s19, 20
	s_add_i32 s35, s20, 24
	v_lshlrev_b64 v[152:153], 13, v[152:153]
; #define LAS __attribute__((address_space(3)))
; template <bool MAPIN>
; __device__ __forceinline__ void transpose_item(const float* W, int K, int N, bf16_t* WT, LAS float* scr, int item, int lane, const float* gk = nullptr) {
;     ...
;     for (int i = 0; i < 32; ++i) { const int kk = 2 * i + (lane >> 5); scr[kk * 33 + (lane & 31)] = W[(size_t)(k0 + kk) * N + n0 + (lane & 31)]; }
;     asm volatile("s_waitcnt lgkmcnt(0)" ::: "memory");
;     const int c = lane & 7;
; #pragma unroll
;     for (int j = 0; j < 4; ++j) { const int n = (lane >> 3) + 8 * j; const LAS float* s = scr + (8 * c) * 33 + n;
;         f32x4 ga = (f32x4){1.f, 1.f, 1.f, 1.f}, gb = ga;
;         if (gk) { ga = *(const f32x4*)(gk + k0 + 8 * c); gb = *(const f32x4*)(gk + k0 + 8 * c + 4); }
	v_lshlrev_b64 v[168:169], 13, v[168:169]
	v_lshl_add_u64 v[136:137], v[2:3], 0, v[182:183]
	v_lshl_add_u64 v[138:139], v[2:3], 0, v[138:139]
	v_lshlrev_b64 v[178:179], 13, v[144:145]
	v_or_b32_e32 v144, s31, v4
	v_mov_b32_e32 v171, v145
	v_mov_b32_e32 v173, v145
	s_add_i32 s34, s19, 24
	s_add_i32 s76, s19, 28
	s_add_i32 s77, s20, 28
	v_or_b32_e32 v170, s28, v5
	v_or_b32_e32 v172, s30, v5
	v_lshl_add_u64 v[152:153], v[2:3], 0, v[152:153]
	v_lshl_add_u64 v[168:169], v[2:3], 0, v[168:169]
	global_load_dword v198, v[136:137], off
	global_load_dword v199, v[152:153], off
	global_load_dword v200, v[138:139], off
	global_load_dword v201, v[168:169], off
	v_lshlrev_b64 v[138:139], 13, v[144:145]
	v_or_b32_e32 v144, s35, v4
	v_mov_b32_e32 v175, v145
	v_mov_b32_e32 v177, v145
	v_or_b32_e32 v174, s34, v5
	v_or_b32_e32 v176, s76, v5
	v_lshlrev_b64 v[170:171], 13, v[170:171]
	v_lshlrev_b64 v[172:173], 13, v[172:173]
	v_lshl_add_u64 v[136:137], v[2:3], 0, v[178:179]
	v_lshl_add_u64 v[138:139], v[2:3], 0, v[138:139]
	v_lshlrev_b64 v[152:153], 13, v[144:145]
	v_or_b32_e32 v144, s77, v4
	v_lshlrev_b64 v[174:175], 13, v[174:175]
	v_lshlrev_b64 v[176:177], 13, v[176:177]
	v_lshl_add_u64 v[170:171], v[2:3], 0, v[170:171]
	v_lshl_add_u64 v[172:173], v[2:3], 0, v[172:173]
	global_load_dword v202, v[136:137], off
	global_load_dword v203, v[170:171], off
	global_load_dword v204, v[138:139], off
	global_load_dword v205, v[172:173], off
	v_lshl_add_u64 v[136:137], v[2:3], 0, v[152:153]
	v_lshlrev_b64 v[138:139], 13, v[144:145]
	v_lshl_add_u64 v[174:175], v[2:3], 0, v[174:175]
	v_lshl_add_u64 v[176:177], v[2:3], 0, v[176:177]
	v_lshl_add_u64 v[138:139], v[2:3], 0, v[138:139]
	global_load_dword v144, v[136:137], off
	global_load_dword v206, v[174:175], off
	global_load_dword v207, v[138:139], off
	global_load_dword v208, v[176:177], off
	v_or_b32_e32 v138, s19, v13
	v_or_b32_e32 v136, s20, v12
	s_add_i32 s17, s17, 16
	s_add_i32 s16, s16, 16
	s_add_i32 s18, s18, -16
	v_mad_u64_u32 v[136:137], s[20:21], v136, s36, v[16:17]
	v_mad_u64_u32 v[138:139], s[20:21], v138, s36, v[16:17]
	v_or_b32_e32 v137, s22, v13
	v_or_b32_e32 v139, s23, v12
	v_or_b32_e32 v172, s24, v13
	v_or_b32_e32 v170, s25, v12
	v_or_b32_e32 v176, s26, v13
	v_or_b32_e32 v174, s27, v12
	v_or_b32_e32 v180, s28, v13
	v_or_b32_e32 v178, s29, v12
	v_or_b32_e32 v184, s30, v13
	v_or_b32_e32 v182, s31, v12
	v_or_b32_e32 v188, s34, v13
	v_or_b32_e32 v186, s35, v12
	v_or_b32_e32 v192, s76, v13
	v_or_b32_e32 v190, s77, v12
	s_cmp_lg_u32 s18, 0
	v_mad_u64_u32 v[152:153], s[20:21], v139, s36, v[16:17]
	v_mad_u64_u32 v[168:169], s[20:21], v137, s36, v[16:17]
	v_mad_u64_u32 v[170:171], s[20:21], v170, s36, v[16:17]
	v_mad_u64_u32 v[172:173], s[20:21], v172, s36, v[16:17]
	v_mad_u64_u32 v[174:175], s[20:21], v174, s36, v[16:17]
	v_mad_u64_u32 v[176:177], s[20:21], v176, s36, v[16:17]
	v_mad_u64_u32 v[178:179], s[20:21], v178, s36, v[16:17]
	v_mad_u64_u32 v[180:181], s[20:21], v180, s36, v[16:17]
	v_mad_u64_u32 v[182:183], s[20:21], v182, s36, v[16:17]
	v_mad_u64_u32 v[184:185], s[20:21], v184, s36, v[16:17]
	v_mad_u64_u32 v[186:187], s[20:21], v186, s36, v[16:17]
	v_mad_u64_u32 v[188:189], s[20:21], v188, s36, v[16:17]
	v_mad_u64_u32 v[190:191], s[20:21], v190, s36, v[16:17]
	v_mad_u64_u32 v[192:193], s[20:21], v192, s36, v[16:17]
	s_waitcnt vmcnt(0)
	ds_write_b32 v6, v21
	ds_write_b32 v8, v25
	ds_write_b32 v22, v65
	ds_write_b32 v38, v67
	ds_write_b32 v40, v68
	ds_write_b32 v42, v69
	ds_write_b32 v44, v70
	ds_write_b32 v46, v71
	ds_write_b32 v48, v72
	ds_write_b32 v50, v73
	ds_write_b32 v52, v74
	ds_write_b32 v54, v75
	ds_write_b32 v56, v14
	ds_write_b32 v58, v76
	ds_write_b32 v60, v77
	ds_write_b32 v62, v78
	ds_write_b32 v136, v151
	ds_write_b32 v138, v155
	ds_write_b32 v152, v195
	ds_write_b32 v168, v197
	ds_write_b32 v170, v198
	ds_write_b32 v172, v199
	ds_write_b32 v174, v200
	ds_write_b32 v176, v201
	ds_write_b32 v178, v202
	ds_write_b32 v180, v203
	ds_write_b32 v182, v204
	ds_write_b32 v184, v205
	ds_write_b32 v186, v144
	ds_write_b32 v188, v206
	ds_write_b32 v190, v207
	ds_write_b32 v192, v208
	s_waitcnt lgkmcnt(0)
	v_lshlrev_b32_e32 v14, 2, v24
	v_cmp_ne_u64_e32 vcc, 0, v[0:1]
	v_lshl_add_u64 v[0:1], v[0:1], 0, v[14:15]
	v_lshlrev_b32_e32 v14, 2, v18
	v_lshl_add_u64 v[22:23], v[0:1], 0, v[14:15]
	v_mov_b32_e32 v0, 1.0
	v_mov_b32_e32 v6, 1.0
	v_mov_b32_e32 v7, 1.0
	v_mov_b32_e32 v8, 1.0
	v_mov_b32_e32 v9, 1.0
	v_mov_b32_e32 v2, 1.0
	v_mov_b32_e32 v3, 1.0
	v_mov_b32_e32 v4, 1.0
	v_mov_b32_e32 v5, 1.0
	v_mov_b32_e32 v102, 1.0
	v_mov_b32_e32 v103, 1.0
	v_mov_b32_e32 v104, 1.0
	v_mov_b32_e32 v105, 1.0
	v_mov_b32_e32 v106, 1.0
	v_mov_b32_e32 v107, 1.0
	v_mov_b32_e32 v108, 1.0
	v_mov_b32_e32 v109, 1.0
	s_and_saveexec_b64 s[16:17], vcc
	s_cbranch_execz .LBB0_111
	global_load_dwordx4 v[102:105], v[22:23], off
	global_load_dwordx4 v[106:109], v[22:23], off offset:16
; #define LAS __attribute__((address_space(3)))
; __device__ __forceinline__ unsigned cvt_pk_bf16(float lo, float hi) { unsigned r; asm volatile("v_cvt_pk_bf16_f32 %0, %1, %2" : "=v"(r) : "v"(lo), "v"(hi)); return r; }
; template <bool MAPIN>
; __device__ __forceinline__ void transpose_item(const float* W, int K, int N, bf16_t* WT, LAS float* scr, int item, int lane, const float* gk = nullptr) {
;     ...
; #pragma unroll
;     for (int j = 0; j < 4; ++j) { const int n = (lane >> 3) + 8 * j; const LAS float* s = scr + (8 * c) * 33 + n;
;         f32x4 ga = (f32x4){1.f, 1.f, 1.f, 1.f}, gb = ga;
;         if (gk) { ga = *(const f32x4*)(gk + k0 + 8 * c); gb = *(const f32x4*)(gk + k0 + 8 * c + 4); }
;         u32x4 o; o.x = cvt_pk_bf16(s[0 * 33] * ga[0], s[1 * 33] * ga[1]); o.y = cvt_pk_bf16(s[2 * 33] * ga[2], s[3 * 33] * ga[3]); o.z = cvt_pk_bf16(s[4 * 33] * gb[0], s[5 * 33] * gb[1]); o.w = cvt_pk_bf16(s[6 * 33] * gb[2], s[7 * 33] * gb[3]);
;         const int nd = MAPIN ? win_map(n0 + n) : (n0 + n);
;         *(u32x4*)(WT + (size_t)nd * K + k0 + 8 * c) = o; }
.LBB0_111:
	s_or_b64 exec, exec, s[16:17]
	ds_read2_b32 v[38:39], v19 offset1:33
	v_lshl_add_u64 v[10:11], v[10:11], 1, s[8:9]
	v_lshlrev_b32_e32 v14, 1, v24
	v_or_b32_e32 v21, v37, v17
	v_lshl_add_u64 v[10:11], v[10:11], 0, v[14:15]
	s_waitcnt vmcnt(0) lgkmcnt(0)
	v_mul_f32_e32 v1, v102, v38
	v_mul_f32_e32 v6, v103, v39
	v_cvt_pk_bf16_f32 v6, v1, v6
	ds_read2_b32 v[38:39], v19 offset0:66 offset1:99
	v_lshlrev_b32_e32 v14, 1, v18
	v_lshl_add_u64 v[24:25], v[10:11], 0, v[14:15]
	v_lshlrev_b32_e32 v14, 12, v21
	v_lshl_add_u64 v[10:11], v[24:25], 0, v[14:15]
	s_waitcnt lgkmcnt(0)
	v_mul_f32_e32 v7, v105, v39
	v_mul_f32_e32 v1, v104, v38
	v_cvt_pk_bf16_f32 v7, v1, v7
	ds_read2_b32 v[8:9], v19 offset0:132 offset1:165
	v_mov_b32_e32 v1, 1.0
	s_waitcnt lgkmcnt(0)
	v_mul_f32_e32 v2, v106, v8
	v_mul_f32_e32 v3, v107, v9
	v_cvt_pk_bf16_f32 v8, v2, v3
	ds_read2_b32 v[2:3], v19 offset0:198 offset1:231
	s_waitcnt lgkmcnt(0)
	v_mul_f32_e32 v2, v108, v2
	v_mul_f32_e32 v3, v109, v3
	v_cvt_pk_bf16_f32 v9, v2, v3
	global_store_dwordx4 v[10:11], v[6:9], off
	v_mov_b32_e32 v2, 1.0
	v_mov_b32_e32 v3, 1.0
	v_mov_b32_e32 v4, 1.0
	v_mov_b32_e32 v5, 1.0
	v_mov_b32_e32 v6, 1.0
	v_mov_b32_e32 v7, 1.0
	s_and_saveexec_b64 s[16:17], vcc
	s_cbranch_execz .LBB0_113
.LBB0_113:
	s_or_b64 exec, exec, s[16:17]
	ds_read2_b32 v[8:9], v19 offset0:8 offset1:41
	v_or_b32_e32 v14, v37, v26
	v_lshlrev_b32_e32 v14, 12, v14
	v_mov_b32_e32 v10, 1.0
	v_mov_b32_e32 v11, 1.0
	s_waitcnt lgkmcnt(0)
	v_mul_f32_e32 v0, v102, v8
	v_mul_f32_e32 v1, v103, v9
	v_cvt_pk_bf16_f32 v38, v0, v1
	ds_read2_b32 v[0:1], v19 offset0:74 offset1:107
	v_mov_b32_e32 v8, 1.0
	v_mov_b32_e32 v9, 1.0
	v_lshl_add_u64 v[42:43], v[24:25], 0, v[14:15]
	s_waitcnt lgkmcnt(0)
	v_mul_f32_e32 v0, v104, v0
	v_mul_f32_e32 v1, v105, v1
	v_cvt_pk_bf16_f32 v39, v0, v1
	ds_read2_b32 v[2:3], v19 offset0:140 offset1:173
	v_mov_b32_e32 v0, 1.0
	s_waitcnt lgkmcnt(0)
	v_mul_f32_e32 v1, v106, v2
	v_mul_f32_e32 v2, v107, v3
	v_cvt_pk_bf16_f32 v40, v1, v2
	ds_read2_b32 v[2:3], v19 offset0:206 offset1:239
	v_mov_b32_e32 v4, 1.0
	v_mov_b32_e32 v5, 1.0
	s_waitcnt lgkmcnt(0)
	v_mul_f32_e32 v1, v108, v2
	v_mul_f32_e32 v2, v109, v3
	v_mov_b32_e32 v6, 1.0
	v_mov_b32_e32 v7, 1.0
	v_cvt_pk_bf16_f32 v41, v1, v2
	global_store_dwordx4 v[42:43], v[38:41], off
	s_and_saveexec_b64 s[16:17], vcc
	s_cbranch_execz .LBB0_115
.LBB0_115:
	s_or_b64 exec, exec, s[16:17]
	ds_read2_b32 v[2:3], v19 offset0:16 offset1:49
	v_or_b32_e32 v14, v37, v27
	v_lshlrev_b32_e32 v14, 12, v14
	v_lshl_add_u64 v[42:43], v[24:25], 0, v[14:15]
	s_waitcnt lgkmcnt(0)
	v_mul_f32_e32 v1, v102, v2
	v_mul_f32_e32 v2, v103, v3
	v_cvt_pk_bf16_f32 v38, v1, v2
	ds_read2_b32 v[2:3], v19 offset0:82 offset1:115
	v_mov_b32_e32 v8, 1.0
	v_mov_b32_e32 v9, 1.0
	s_waitcnt lgkmcnt(0)
	v_mul_f32_e32 v1, v104, v2
	v_mul_f32_e32 v2, v105, v3
	v_cvt_pk_bf16_f32 v39, v1, v2
	ds_read2_b32 v[10:11], v19 offset0:148 offset1:181
	v_mov_b32_e32 v1, 1.0
	v_mov_b32_e32 v2, 1.0
	v_mov_b32_e32 v3, 1.0
	s_waitcnt lgkmcnt(0)
	v_mul_f32_e32 v4, v106, v10
	v_mul_f32_e32 v5, v107, v11
	v_cvt_pk_bf16_f32 v40, v4, v5
	ds_read2_b32 v[4:5], v19 offset0:214 offset1:247
	v_mov_b32_e32 v10, 1.0
	v_mov_b32_e32 v11, 1.0
	s_waitcnt lgkmcnt(0)
	v_mul_f32_e32 v4, v108, v4
	v_mul_f32_e32 v5, v109, v5
	v_cvt_pk_bf16_f32 v41, v4, v5
	global_store_dwordx4 v[42:43], v[38:41], off
	s_and_saveexec_b64 s[16:17], vcc
	s_cbranch_execz .LBB0_117
.LBB0_117:
	s_or_b64 exec, exec, s[16:17]
	ds_read2_b32 v[4:5], v19 offset0:24 offset1:57
	s_waitcnt lgkmcnt(0)
	v_mul_f32_e32 v0, v102, v4
	v_mul_f32_e32 v1, v103, v5
	v_cvt_pk_bf16_f32 v0, v0, v1
	ds_read2_b32 v[4:5], v19 offset0:90 offset1:123
	s_waitcnt lgkmcnt(0)
	v_mul_f32_e32 v1, v104, v4
	v_mul_f32_e32 v2, v105, v5
	v_cvt_pk_bf16_f32 v1, v1, v2
	ds_read2_b32 v[2:3], v19 offset0:156 offset1:189
	s_waitcnt lgkmcnt(0)
	v_mul_f32_e32 v2, v106, v2
	v_mul_f32_e32 v3, v107, v3
	v_cvt_pk_bf16_f32 v2, v2, v3
	ds_read2_b32 v[4:5], v19 offset0:222 offset1:255
	v_or_b32_e32 v3, v37, v28
	v_lshlrev_b32_e32 v14, 12, v3
	s_waitcnt lgkmcnt(0)
	v_mul_f32_e32 v3, v108, v4
	v_mul_f32_e32 v4, v109, v5
	v_cvt_pk_bf16_f32 v3, v3, v4
	v_lshl_add_u64 v[4:5], v[24:25], 0, v[14:15]
	global_store_dwordx4 v[4:5], v[0:3], off
	s_waitcnt lgkmcnt(0)

; template <bool MAPIN>
; __device__ __forceinline__ void transpose_item(const float* W, int K, int N, bf16_t* WT, LAS float* scr, int item, int lane, const float* gk = nullptr) {
;     const int nblk = N / 32, kb = item / nblk, nb = item % nblk, k0 = 64 * kb, n0 = 32 * nb;
; #pragma unroll 8
;     for (int i = 0; i < 32; ++i) { const int kk = 2 * i + (lane >> 5); scr[kk * 33 + (lane & 31)] = W[(size_t)(k0 + kk) * N + n0 + (lane & 31)]; }
.LBB0_120:
	s_lshl_b32 s19, s0, 1
	s_lshl_b32 s20, s1, 1
	v_or_b32_e32 v2, s19, v13
	v_or_b32_e32 v11, s20, v12
	s_add_i32 s21, s19, 4
	s_add_i32 s22, s20, 4
	s_add_i32 s23, s19, 8
	s_add_i32 s24, s20, 8
	s_add_i32 s25, s19, 12
	s_add_i32 s26, s20, 12
	s_add_i32 s27, s19, 16
	s_add_i32 s28, s20, 16
	s_add_i32 s29, s19, 20
	s_add_i32 s30, s20, 20
	s_add_i32 s31, s19, 24
	s_add_i32 s34, s20, 24
	s_add_i32 s19, s19, 28
	s_add_i32 s20, s20, 28
	v_add_u32_e32 v4, v11, v24
	v_or_b32_e32 v14, s21, v13
	v_or_b32_e32 v21, s22, v12
	v_or_b32_e32 v25, s23, v13
	v_or_b32_e32 v62, s24, v12
	v_or_b32_e32 v63, s25, v13
	v_or_b32_e32 v65, s26, v12
	v_or_b32_e32 v67, s27, v13
	v_or_b32_e32 v68, s28, v12
	v_or_b32_e32 v69, s29, v13
	v_or_b32_e32 v70, s30, v12
	v_or_b32_e32 v71, s31, v13
	v_or_b32_e32 v72, s34, v12
	v_or_b32_e32 v73, s19, v13
	v_or_b32_e32 v74, s20, v12
	v_add_u32_e32 v5, v2, v3
	v_mul_lo_u32 v4, v4, s46
	v_add_u32_e32 v9, v14, v3
	v_add_u32_e32 v8, v21, v24
	v_add_u32_e32 v23, v25, v3
	v_add_u32_e32 v38, v62, v24
	v_add_u32_e32 v39, v63, v3
	v_add_u32_e32 v41, v65, v24
	v_add_u32_e32 v43, v67, v3
	v_add_u32_e32 v45, v68, v24
	v_add_u32_e32 v47, v69, v3
	v_add_u32_e32 v49, v70, v24
	v_add_u32_e32 v51, v71, v3
	v_add_u32_e32 v53, v72, v24
	v_add_u32_e32 v55, v73, v3
	v_add_u32_e32 v57, v74, v24
	v_mul_lo_u32 v6, v5, s46
	v_ashrrev_i32_e32 v5, 31, v4
	v_mul_lo_u32 v8, v8, s46
	v_mul_lo_u32 v22, v9, s46
	v_mul_lo_u32 v38, v38, s46
	v_mul_lo_u32 v40, v23, s46
	v_mul_lo_u32 v42, v41, s46
	v_mul_lo_u32 v44, v39, s46
	v_mul_lo_u32 v46, v45, s46
	v_mul_lo_u32 v48, v43, s46
	v_mul_lo_u32 v50, v49, s46
	v_mul_lo_u32 v52, v47, s46
	v_mul_lo_u32 v54, v53, s46
	v_mul_lo_u32 v56, v51, s46
	v_mul_lo_u32 v58, v57, s46
	v_mul_lo_u32 v60, v55, s46
	v_ashrrev_i32_e32 v7, 31, v6
	v_lshl_add_u64 v[4:5], v[0:1], 0, v[4:5]
	v_ashrrev_i32_e32 v23, 31, v22
	v_ashrrev_i32_e32 v9, 31, v8
	v_ashrrev_i32_e32 v41, 31, v40
	v_ashrrev_i32_e32 v39, 31, v38
	v_ashrrev_i32_e32 v45, 31, v44
	v_ashrrev_i32_e32 v43, 31, v42
	v_ashrrev_i32_e32 v49, 31, v48
	v_ashrrev_i32_e32 v47, 31, v46
	v_ashrrev_i32_e32 v53, 31, v52
	v_ashrrev_i32_e32 v51, 31, v50
	v_ashrrev_i32_e32 v57, 31, v56
	v_ashrrev_i32_e32 v55, 31, v54
	v_ashrrev_i32_e32 v61, 31, v60
	v_ashrrev_i32_e32 v59, 31, v58
	v_lshl_add_u64 v[6:7], v[0:1], 0, v[6:7]
	v_lshl_add_u64 v[8:9], v[0:1], 0, v[8:9]
	v_lshl_add_u64 v[22:23], v[0:1], 0, v[22:23]
	v_lshl_add_u64 v[38:39], v[0:1], 0, v[38:39]
	v_lshl_add_u64 v[40:41], v[0:1], 0, v[40:41]
	v_lshl_add_u64 v[42:43], v[0:1], 0, v[42:43]
	v_lshl_add_u64 v[44:45], v[0:1], 0, v[44:45]
	v_lshl_add_u64 v[46:47], v[0:1], 0, v[46:47]
	v_lshl_add_u64 v[48:49], v[0:1], 0, v[48:49]
	v_lshl_add_u64 v[50:51], v[0:1], 0, v[50:51]
	v_lshl_add_u64 v[52:53], v[0:1], 0, v[52:53]
	v_lshl_add_u64 v[54:55], v[0:1], 0, v[54:55]
	v_lshl_add_u64 v[56:57], v[0:1], 0, v[56:57]
	v_lshl_add_u64 v[58:59], v[0:1], 0, v[58:59]
	v_lshl_add_u64 v[60:61], v[0:1], 0, v[60:61]
	global_load_dword v75, v[4:5], off
	global_load_dword v76, v[6:7], off
	global_load_dword v77, v[8:9], off
	global_load_dword v78, v[22:23], off
	global_load_dword v79, v[38:39], off
	global_load_dword v80, v[40:41], off
	global_load_dword v81, v[42:43], off
	global_load_dword v82, v[44:45], off
	global_load_dword v83, v[46:47], off
	global_load_dword v84, v[48:49], off
	global_load_dword v85, v[50:51], off
	global_load_dword v86, v[52:53], off
	global_load_dword v87, v[54:55], off
	global_load_dword v88, v[56:57], off
	global_load_dword v89, v[58:59], off
	global_load_dword v90, v[60:61], off
	s_add_i32 s1, s1, 16
	s_add_i32 s0, s0, 16
	s_add_i32 s18, s18, -16
	v_mad_u64_u32 v[4:5], s[20:21], v11, s36, v[16:17]
	s_cmp_lg_u32 s18, 0
	v_mad_u64_u32 v[6:7], s[20:21], v2, s36, v[16:17]
	v_mad_u64_u32 v[8:9], s[20:21], v21, s36, v[16:17]
	v_mad_u64_u32 v[22:23], s[20:21], v14, s36, v[16:17]
	v_mad_u64_u32 v[38:39], s[20:21], v62, s36, v[16:17]
	v_mad_u64_u32 v[40:41], s[20:21], v25, s36, v[16:17]
	v_mad_u64_u32 v[42:43], s[20:21], v65, s36, v[16:17]
	v_mad_u64_u32 v[44:45], s[20:21], v63, s36, v[16:17]
	v_mad_u64_u32 v[46:47], s[20:21], v68, s36, v[16:17]
	v_mad_u64_u32 v[48:49], s[20:21], v67, s36, v[16:17]
	v_mad_u64_u32 v[50:51], s[20:21], v70, s36, v[16:17]
	v_mad_u64_u32 v[52:53], s[20:21], v69, s36, v[16:17]
	v_mad_u64_u32 v[54:55], s[20:21], v72, s36, v[16:17]
	v_mad_u64_u32 v[56:57], s[20:21], v71, s36, v[16:17]
	v_mad_u64_u32 v[58:59], s[20:21], v74, s36, v[16:17]
	v_mad_u64_u32 v[60:61], s[20:21], v73, s36, v[16:17]
	s_lshl_b32 s19, s0, 1
	s_lshl_b32 s20, s1, 1
	v_or_b32_e32 v132, s19, v13
	v_or_b32_e32 v141, s20, v12
	s_add_i32 s21, s19, 4
	s_add_i32 s22, s20, 4
	s_add_i32 s23, s19, 8
	s_add_i32 s24, s20, 8
	s_add_i32 s25, s19, 12
	s_add_i32 s26, s20, 12
	s_add_i32 s27, s19, 16
	s_add_i32 s28, s20, 16
	s_add_i32 s29, s19, 20
	s_add_i32 s30, s20, 20
	s_add_i32 s31, s19, 24
	s_add_i32 s34, s20, 24
	s_add_i32 s19, s19, 28
	s_add_i32 s20, s20, 28
	v_add_u32_e32 v134, v141, v24
	v_or_b32_e32 v144, s21, v13
	v_or_b32_e32 v151, s22, v12
	v_or_b32_e32 v155, s23, v13
	v_or_b32_e32 v192, s24, v12
	v_or_b32_e32 v193, s25, v13
	v_or_b32_e32 v195, s26, v12
	v_or_b32_e32 v197, s27, v13
	v_or_b32_e32 v198, s28, v12
	v_or_b32_e32 v199, s29, v13
	v_or_b32_e32 v200, s30, v12
	v_or_b32_e32 v201, s31, v13
	v_or_b32_e32 v202, s34, v12
	v_or_b32_e32 v203, s19, v13
	v_or_b32_e32 v204, s20, v12
	v_add_u32_e32 v135, v132, v3
	v_mul_lo_u32 v134, v134, s46
	v_add_u32_e32 v139, v144, v3
	v_add_u32_e32 v138, v151, v24
	v_add_u32_e32 v153, v155, v3
	v_add_u32_e32 v168, v192, v24
	v_add_u32_e32 v169, v193, v3
	v_add_u32_e32 v171, v195, v24
	v_add_u32_e32 v173, v197, v3
; #define LAS __attribute__((address_space(3)))
; template <bool MAPIN>
; __device__ __forceinline__ void transpose_item(const float* W, int K, int N, bf16_t* WT, LAS float* scr, int item, int lane, const float* gk = nullptr) {
;     ...
;     for (int i = 0; i < 32; ++i) { const int kk = 2 * i + (lane >> 5); scr[kk * 33 + (lane & 31)] = W[(size_t)(k0 + kk) * N + n0 + (lane & 31)]; }
;     asm volatile("s_waitcnt lgkmcnt(0)" ::: "memory");
;     const int c = lane & 7;
; #pragma unroll
;     for (int j = 0; j < 4; ++j) { const int n = (lane >> 3) + 8 * j; const LAS float* s = scr + (8 * c) * 33 + n;
;         f32x4 ga = (f32x4){1.f, 1.f, 1.f, 1.f}, gb = ga;
;         if (gk) { ga = *(const f32x4*)(gk + k0 + 8 * c); gb = *(const f32x4*)(gk + k0 + 8 * c + 4); }
	v_add_u32_e32 v175, v198, v24
	v_add_u32_e32 v177, v199, v3
	v_add_u32_e32 v179, v200, v24
	v_add_u32_e32 v181, v201, v3
	v_add_u32_e32 v183, v202, v24
	v_add_u32_e32 v185, v203, v3
	v_add_u32_e32 v187, v204, v24
	v_mul_lo_u32 v136, v135, s46
	v_ashrrev_i32_e32 v135, 31, v134
	v_mul_lo_u32 v138, v138, s46
	v_mul_lo_u32 v152, v139, s46
	v_mul_lo_u32 v168, v168, s46
	v_mul_lo_u32 v170, v153, s46
	v_mul_lo_u32 v172, v171, s46
	v_mul_lo_u32 v174, v169, s46
	v_mul_lo_u32 v176, v175, s46
	v_mul_lo_u32 v178, v173, s46
	v_mul_lo_u32 v180, v179, s46
	v_mul_lo_u32 v182, v177, s46
	v_mul_lo_u32 v184, v183, s46
	v_mul_lo_u32 v186, v181, s46
	v_mul_lo_u32 v188, v187, s46
	v_mul_lo_u32 v190, v185, s46
	v_ashrrev_i32_e32 v137, 31, v136
	v_lshl_add_u64 v[134:135], v[0:1], 0, v[134:135]
	v_ashrrev_i32_e32 v153, 31, v152
	v_ashrrev_i32_e32 v139, 31, v138
	v_ashrrev_i32_e32 v171, 31, v170
	v_ashrrev_i32_e32 v169, 31, v168
	v_ashrrev_i32_e32 v175, 31, v174
	v_ashrrev_i32_e32 v173, 31, v172
	v_ashrrev_i32_e32 v179, 31, v178
	v_ashrrev_i32_e32 v177, 31, v176
	v_ashrrev_i32_e32 v183, 31, v182
	v_ashrrev_i32_e32 v181, 31, v180
	v_ashrrev_i32_e32 v187, 31, v186
	v_ashrrev_i32_e32 v185, 31, v184
	v_ashrrev_i32_e32 v191, 31, v190
	v_ashrrev_i32_e32 v189, 31, v188
	v_lshl_add_u64 v[136:137], v[0:1], 0, v[136:137]
	v_lshl_add_u64 v[138:139], v[0:1], 0, v[138:139]
	v_lshl_add_u64 v[152:153], v[0:1], 0, v[152:153]
	v_lshl_add_u64 v[168:169], v[0:1], 0, v[168:169]
	v_lshl_add_u64 v[170:171], v[0:1], 0, v[170:171]
	v_lshl_add_u64 v[172:173], v[0:1], 0, v[172:173]
	v_lshl_add_u64 v[174:175], v[0:1], 0, v[174:175]
	v_lshl_add_u64 v[176:177], v[0:1], 0, v[176:177]
	v_lshl_add_u64 v[178:179], v[0:1], 0, v[178:179]
	v_lshl_add_u64 v[180:181], v[0:1], 0, v[180:181]
	v_lshl_add_u64 v[182:183], v[0:1], 0, v[182:183]
	v_lshl_add_u64 v[184:185], v[0:1], 0, v[184:185]
	v_lshl_add_u64 v[186:187], v[0:1], 0, v[186:187]
	v_lshl_add_u64 v[188:189], v[0:1], 0, v[188:189]
	v_lshl_add_u64 v[190:191], v[0:1], 0, v[190:191]
	global_load_dword v205, v[134:135], off
	global_load_dword v206, v[136:137], off
	global_load_dword v207, v[138:139], off
	global_load_dword v208, v[152:153], off
	global_load_dword v209, v[168:169], off
	global_load_dword v210, v[170:171], off
	global_load_dword v211, v[172:173], off
	global_load_dword v212, v[174:175], off
	global_load_dword v213, v[176:177], off
	global_load_dword v214, v[178:179], off
	global_load_dword v215, v[180:181], off
	global_load_dword v216, v[182:183], off
	global_load_dword v217, v[184:185], off
	global_load_dword v218, v[186:187], off
	global_load_dword v219, v[188:189], off
	global_load_dword v220, v[190:191], off
	s_add_i32 s1, s1, 16
	s_add_i32 s0, s0, 16
	s_add_i32 s18, s18, -16
	v_mad_u64_u32 v[134:135], s[20:21], v141, s36, v[16:17]
	s_cmp_lg_u32 s18, 0
	v_mad_u64_u32 v[136:137], s[20:21], v132, s36, v[16:17]
	v_mad_u64_u32 v[138:139], s[20:21], v151, s36, v[16:17]
	v_mad_u64_u32 v[152:153], s[20:21], v144, s36, v[16:17]
	v_mad_u64_u32 v[168:169], s[20:21], v192, s36, v[16:17]
	v_mad_u64_u32 v[170:171], s[20:21], v155, s36, v[16:17]
	v_mad_u64_u32 v[172:173], s[20:21], v195, s36, v[16:17]
	v_mad_u64_u32 v[174:175], s[20:21], v193, s36, v[16:17]
	v_mad_u64_u32 v[176:177], s[20:21], v198, s36, v[16:17]
	v_mad_u64_u32 v[178:179], s[20:21], v197, s36, v[16:17]
	v_mad_u64_u32 v[180:181], s[20:21], v200, s36, v[16:17]
	v_mad_u64_u32 v[182:183], s[20:21], v199, s36, v[16:17]
	v_mad_u64_u32 v[184:185], s[20:21], v202, s36, v[16:17]
	v_mad_u64_u32 v[186:187], s[20:21], v201, s36, v[16:17]
	v_mad_u64_u32 v[188:189], s[20:21], v204, s36, v[16:17]
	v_mad_u64_u32 v[190:191], s[20:21], v203, s36, v[16:17]
	s_waitcnt vmcnt(0)
	ds_write_b32 v4, v75
	ds_write_b32 v6, v76
	ds_write_b32 v8, v77
	ds_write_b32 v22, v78
	ds_write_b32 v38, v79
	ds_write_b32 v40, v80
	ds_write_b32 v42, v81
	ds_write_b32 v44, v82
	ds_write_b32 v46, v83
	ds_write_b32 v48, v84
	ds_write_b32 v50, v85
	ds_write_b32 v52, v86
	ds_write_b32 v54, v87
	ds_write_b32 v56, v88
	ds_write_b32 v58, v89
	ds_write_b32 v60, v90
	ds_write_b32 v134, v205
	ds_write_b32 v136, v206
	ds_write_b32 v138, v207
	ds_write_b32 v152, v208
	ds_write_b32 v168, v209
	ds_write_b32 v170, v210
	ds_write_b32 v172, v211
	ds_write_b32 v174, v212
	ds_write_b32 v176, v213
	ds_write_b32 v178, v214
	ds_write_b32 v180, v215
	ds_write_b32 v182, v216
	ds_write_b32 v184, v217
	ds_write_b32 v186, v218
	ds_write_b32 v188, v219
	ds_write_b32 v190, v220
	v_add_u32_e32 v0, 0xffffc400, v36
	v_cmp_lt_u32_e32 vcc, s47, v0
	v_mov_b32_e32 v1, s40
	v_cmp_gt_u32_e64 s[0:1], s48, v0
	v_mov_b32_e32 v0, s39
	s_waitcnt lgkmcnt(0)
	v_ashrrev_i32_e32 v25, 31, v24
	v_cndmask_b32_e64 v1, v1, 0, s[0:1]
	v_cndmask_b32_e64 v0, v0, 0, s[0:1]
	v_lshl_add_u64 v[0:1], v[24:25], 2, v[0:1]
	v_lshlrev_b32_e32 v14, 2, v18
	v_lshl_add_u64 v[22:23], v[0:1], 0, v[14:15]
	v_mov_b32_e32 v6, 1.0
	v_mov_b32_e32 v7, 1.0
	v_mov_b32_e32 v8, 1.0
	v_mov_b32_e32 v9, 1.0
	v_mov_b32_e32 v2, 1.0
	v_mov_b32_e32 v3, 1.0
	v_mov_b32_e32 v4, 1.0
	v_mov_b32_e32 v5, 1.0
	v_mov_b32_e32 v102, 1.0
	v_mov_b32_e32 v103, 1.0
	v_mov_b32_e32 v104, 1.0
	v_mov_b32_e32 v105, 1.0
	v_mov_b32_e32 v106, 1.0
	v_mov_b32_e32 v107, 1.0
	v_mov_b32_e32 v108, 1.0
	v_mov_b32_e32 v109, 1.0
	s_and_saveexec_b64 s[0:1], vcc
	s_cbranch_execz .LBB0_123
	global_load_dwordx4 v[102:105], v[22:23], off
	global_load_dwordx4 v[106:109], v[22:23], off offset:16
; #define LAS __attribute__((address_space(3)))
; __device__ __forceinline__ unsigned cvt_pk_bf16(float lo, float hi) { unsigned r; asm volatile("v_cvt_pk_bf16_f32 %0, %1, %2" : "=v"(r) : "v"(lo), "v"(hi)); return r; }
; __device__ __forceinline__ int win_map(int n) {
;     if (n < 1024) { const int d = n & 63; return (n & ~63) + 2 * (d & 31) + (d >> 5); }
;     if (n < 1280) { const int q = n - 1024, d = q & 63; return 2048 + (q & ~63) + 2 * (d & 31) + (d >> 5); }
;     if (n < 1536) return 2304 + (n - 1280);
;     if (n < 2560) return 2560 + (n - 1536);
;     if (n < 3072) return 1024 + (n - 2560);
;     if (n < 3584) { const int ch = n - 3072; return 4608 + 256 * (ch >> 7) + (ch & 127); }
;     if (n < 4096) { const int ch = n - 3584; return 4608 + 256 * (ch >> 7) + 128 + (ch & 127); }
;     if (n < 4608) return 3584 + (n - 4096);
;     if (n < 5120) return 1536 + (n - 4608);
;     return 4096 + (n - 5120);
; template <bool MAPIN>
; __device__ __forceinline__ void transpose_item(const float* W, int K, int N, bf16_t* WT, LAS float* scr, int item, int lane, const float* gk = nullptr) {
;     ...
; #pragma unroll
;     for (int j = 0; j < 4; ++j) { const int n = (lane >> 3) + 8 * j; const LAS float* s = scr + (8 * c) * 33 + n;
;         f32x4 ga = (f32x4){1.f, 1.f, 1.f, 1.f}, gb = ga;
;         if (gk) { ga = *(const f32x4*)(gk + k0 + 8 * c); gb = *(const f32x4*)(gk + k0 + 8 * c + 4); }
;         u32x4 o; o.x = cvt_pk_bf16(s[0 * 33] * ga[0], s[1 * 33] * ga[1]); o.y = cvt_pk_bf16(s[2 * 33] * ga[2], s[3 * 33] * ga[3]); o.z = cvt_pk_bf16(s[4 * 33] * gb[0], s[5 * 33] * gb[1]); o.w = cvt_pk_bf16(s[6 * 33] * gb[2], s[7 * 33] * gb[3]);
;         const int nd = MAPIN ? win_map(n0 + n) : (n0 + n);
;         *(u32x4*)(WT + (size_t)nd * K + k0 + 8 * c) = o; }
.LBB0_123:
	s_or_b64 exec, exec, s[0:1]
	ds_read2_b32 v[0:1], v19 offset1:33
	s_waitcnt vmcnt(0) lgkmcnt(0)
	v_mul_f32_e32 v0, v102, v0
	v_mul_f32_e32 v1, v103, v1
	v_cvt_pk_bf16_f32 v0, v0, v1
	ds_read2_b32 v[6:7], v19 offset0:66 offset1:99
	s_waitcnt lgkmcnt(0)
	v_mul_f32_e32 v1, v104, v6
	v_mul_f32_e32 v6, v105, v7
	v_cvt_pk_bf16_f32 v1, v1, v6
	ds_read2_b32 v[6:7], v19 offset0:132 offset1:165
	s_waitcnt lgkmcnt(0)
	v_mul_f32_e32 v2, v106, v6
	v_mul_f32_e32 v3, v107, v7
	v_cvt_pk_bf16_f32 v2, v2, v3
	ds_read2_b32 v[8:9], v19 offset0:198 offset1:231
	v_and_b32_e32 v6, 1, v37
	v_or_b32_e32 v7, v10, v17
	v_and_or_b32 v3, v10, s49, v6
	v_add_u32_e32 v11, 0x400, v3
	s_waitcnt lgkmcnt(0)
	v_mul_f32_e32 v3, v108, v8
	v_mul_f32_e32 v4, v109, v9
	v_cmp_lt_i32_e64 s[0:1], s43, v7
	v_cvt_pk_bf16_f32 v3, v3, v4
	s_and_saveexec_b64 s[18:19], s[0:1]
	s_xor_b64 s[18:19], exec, s[18:19]
	s_cbranch_execz .LBB0_157
	v_cmp_lt_u32_e64 s[0:1], s51, v10
	s_and_saveexec_b64 s[20:21], s[0:1]
	s_xor_b64 s[20:21], exec, s[20:21]
	s_cbranch_execz .LBB0_154
	v_cmp_lt_u32_e64 s[0:1], s44, v10
	s_and_saveexec_b64 s[22:23], s[0:1]
	s_xor_b64 s[22:23], exec, s[22:23]
	s_cbranch_execz .LBB0_151
	v_cmp_lt_u32_e64 s[0:1], s56, v10
	s_and_saveexec_b64 s[24:25], s[0:1]
	s_xor_b64 s[24:25], exec, s[24:25]
	s_cbranch_execz .LBB0_148
	v_cmp_lt_u32_e64 s[0:1], s57, v10
	s_and_saveexec_b64 s[26:27], s[0:1]
	s_xor_b64 s[26:27], exec, s[26:27]
	s_cbranch_execz .LBB0_145
	v_cmp_lt_u32_e64 s[0:1], s58, v10
	s_and_saveexec_b64 s[28:29], s[0:1]
	s_xor_b64 s[28:29], exec, s[28:29]
	s_cbranch_execz .LBB0_142
	v_cmp_lt_u32_e64 s[0:1], s59, v10
	s_and_saveexec_b64 s[30:31], s[0:1]
	s_xor_b64 s[30:31], exec, s[30:31]
	s_cbranch_execz .LBB0_139
	v_cmp_lt_u32_e64 s[0:1], s72, v10
	s_and_saveexec_b64 s[34:35], s[0:1]
	s_xor_b64 s[34:35], exec, s[34:35]
	s_cbranch_execz .LBB0_136
	v_cmp_lt_u32_e64 s[0:1], s73, v10
	s_and_saveexec_b64 s[76:77], s[0:1]
	s_xor_b64 s[0:1], exec, s[76:77]
	v_add_u32_e32 v4, 0xfffffc00, v7
	s_andn2_saveexec_b64 s[0:1], s[0:1]
	v_add_u32_e32 v4, 0xfffff400, v7
	s_or_b64 exec, exec, s[0:1]

; #define LAS __attribute__((address_space(3)))
; __device__ __forceinline__ unsigned cvt_pk_bf16(float lo, float hi) { unsigned r; asm volatile("v_cvt_pk_bf16_f32 %0, %1, %2" : "=v"(r) : "v"(lo), "v"(hi)); return r; }
; __device__ __forceinline__ int win_map(int n) {
;     if (n < 1024) { const int d = n & 63; return (n & ~63) + 2 * (d & 31) + (d >> 5); }
;     if (n < 1280) { const int q = n - 1024, d = q & 63; return 2048 + (q & ~63) + 2 * (d & 31) + (d >> 5); }
;     if (n < 1536) return 2304 + (n - 1280);
;     if (n < 2560) return 2560 + (n - 1536);
;     if (n < 3072) return 1024 + (n - 2560);
;     if (n < 3584) { const int ch = n - 3072; return 4608 + 256 * (ch >> 7) + (ch & 127); }
;     if (n < 4096) { const int ch = n - 3584; return 4608 + 256 * (ch >> 7) + 128 + (ch & 127); }
;     if (n < 4608) return 3584 + (n - 4096);
;     if (n < 5120) return 1536 + (n - 4608);
;     return 4096 + (n - 5120);
; template <bool MAPIN>
; __device__ __forceinline__ void transpose_item(const float* W, int K, int N, bf16_t* WT, LAS float* scr, int item, int lane, const float* gk = nullptr) {
;     ...
; #pragma unroll
;     for (int j = 0; j < 4; ++j) { const int n = (lane >> 3) + 8 * j; const LAS float* s = scr + (8 * c) * 33 + n;
;         f32x4 ga = (f32x4){1.f, 1.f, 1.f, 1.f}, gb = ga;
;         if (gk) { ga = *(const f32x4*)(gk + k0 + 8 * c); gb = *(const f32x4*)(gk + k0 + 8 * c + 4); }
;         u32x4 o; o.x = cvt_pk_bf16(s[0 * 33] * ga[0], s[1 * 33] * ga[1]); o.y = cvt_pk_bf16(s[2 * 33] * ga[2], s[3 * 33] * ga[3]); o.z = cvt_pk_bf16(s[4 * 33] * gb[0], s[5 * 33] * gb[1]); o.w = cvt_pk_bf16(s[6 * 33] * gb[2], s[7 * 33] * gb[3]);
;         const int nd = MAPIN ? win_map(n0 + n) : (n0 + n);
;         *(u32x4*)(WT + (size_t)nd * K + k0 + 8 * c) = o; }
.LBB0_161:
	s_or_b64 exec, exec, s[0:1]
	ds_read2_b32 v[0:1], v19 offset0:8 offset1:41
	s_waitcnt lgkmcnt(0)
	v_mul_f32_e32 v0, v102, v0
	v_mul_f32_e32 v1, v103, v1
	v_cvt_pk_bf16_f32 v0, v0, v1
	ds_read2_b32 v[6:7], v19 offset0:74 offset1:107
	s_waitcnt lgkmcnt(0)
	v_mul_f32_e32 v1, v104, v6
	v_mul_f32_e32 v6, v105, v7
	v_cvt_pk_bf16_f32 v1, v1, v6
	ds_read2_b32 v[6:7], v19 offset0:140 offset1:173
	s_waitcnt lgkmcnt(0)
	v_mul_f32_e32 v2, v106, v6
	v_mul_f32_e32 v3, v107, v7
	v_cvt_pk_bf16_f32 v2, v2, v3
	ds_read2_b32 v[8:9], v19 offset0:206 offset1:239
	v_or_b32_e32 v6, v10, v26
	v_cmp_lt_i32_e64 s[0:1], s43, v6
	s_waitcnt lgkmcnt(0)
	v_mul_f32_e32 v3, v108, v8
	v_mul_f32_e32 v4, v109, v9
	v_cvt_pk_bf16_f32 v3, v3, v4
	s_and_saveexec_b64 s[18:19], s[0:1]
	s_xor_b64 s[18:19], exec, s[18:19]
	s_cbranch_execz .LBB0_195
	v_cmp_lt_u32_e64 s[0:1], s51, v10
	s_and_saveexec_b64 s[20:21], s[0:1]
	s_xor_b64 s[20:21], exec, s[20:21]
	s_cbranch_execz .LBB0_192
	v_cmp_lt_u32_e64 s[0:1], s44, v10
	s_and_saveexec_b64 s[22:23], s[0:1]
	s_xor_b64 s[22:23], exec, s[22:23]
	s_cbranch_execz .LBB0_189
	v_cmp_lt_u32_e64 s[0:1], s56, v10
	s_and_saveexec_b64 s[24:25], s[0:1]
	s_xor_b64 s[24:25], exec, s[24:25]
	s_cbranch_execz .LBB0_186
	v_cmp_lt_u32_e64 s[0:1], s57, v10
	s_and_saveexec_b64 s[26:27], s[0:1]
	s_xor_b64 s[26:27], exec, s[26:27]
	s_cbranch_execz .LBB0_183
	v_cmp_lt_u32_e64 s[0:1], s58, v10
	s_and_saveexec_b64 s[28:29], s[0:1]
	s_xor_b64 s[28:29], exec, s[28:29]
	s_cbranch_execz .LBB0_180
	v_cmp_lt_u32_e64 s[0:1], s59, v10
	s_and_saveexec_b64 s[30:31], s[0:1]
	s_xor_b64 s[30:31], exec, s[30:31]
	s_cbranch_execz .LBB0_177
	v_cmp_lt_u32_e64 s[0:1], s72, v10
	s_and_saveexec_b64 s[34:35], s[0:1]
	s_xor_b64 s[34:35], exec, s[34:35]
	s_cbranch_execz .LBB0_174
	v_cmp_lt_u32_e64 s[0:1], s73, v10
	s_and_saveexec_b64 s[76:77], s[0:1]
	s_xor_b64 s[0:1], exec, s[76:77]
	v_add_u32_e32 v4, 0xfffffc00, v6
	s_andn2_saveexec_b64 s[0:1], s[0:1]
	v_add_u32_e32 v4, 0xfffff400, v6
	s_or_b64 exec, exec, s[0:1]

; #define LAS __attribute__((address_space(3)))
; __device__ __forceinline__ unsigned cvt_pk_bf16(float lo, float hi) { unsigned r; asm volatile("v_cvt_pk_bf16_f32 %0, %1, %2" : "=v"(r) : "v"(lo), "v"(hi)); return r; }
; __device__ __forceinline__ int win_map(int n) {
;     if (n < 1024) { const int d = n & 63; return (n & ~63) + 2 * (d & 31) + (d >> 5); }
;     if (n < 1280) { const int q = n - 1024, d = q & 63; return 2048 + (q & ~63) + 2 * (d & 31) + (d >> 5); }
;     if (n < 1536) return 2304 + (n - 1280);
;     if (n < 2560) return 2560 + (n - 1536);
;     if (n < 3072) return 1024 + (n - 2560);
;     if (n < 3584) { const int ch = n - 3072; return 4608 + 256 * (ch >> 7) + (ch & 127); }
;     if (n < 4096) { const int ch = n - 3584; return 4608 + 256 * (ch >> 7) + 128 + (ch & 127); }
;     if (n < 4608) return 3584 + (n - 4096);
;     if (n < 5120) return 1536 + (n - 4608);
;     return 4096 + (n - 5120);
; template <bool MAPIN>
; __device__ __forceinline__ void transpose_item(const float* W, int K, int N, bf16_t* WT, LAS float* scr, int item, int lane, const float* gk = nullptr) {
;     ...
; #pragma unroll
;     for (int j = 0; j < 4; ++j) { const int n = (lane >> 3) + 8 * j; const LAS float* s = scr + (8 * c) * 33 + n;
;         f32x4 ga = (f32x4){1.f, 1.f, 1.f, 1.f}, gb = ga;
;         if (gk) { ga = *(const f32x4*)(gk + k0 + 8 * c); gb = *(const f32x4*)(gk + k0 + 8 * c + 4); }
;         u32x4 o; o.x = cvt_pk_bf16(s[0 * 33] * ga[0], s[1 * 33] * ga[1]); o.y = cvt_pk_bf16(s[2 * 33] * ga[2], s[3 * 33] * ga[3]); o.z = cvt_pk_bf16(s[4 * 33] * gb[0], s[5 * 33] * gb[1]); o.w = cvt_pk_bf16(s[6 * 33] * gb[2], s[7 * 33] * gb[3]);
;         const int nd = MAPIN ? win_map(n0 + n) : (n0 + n);
;         *(u32x4*)(WT + (size_t)nd * K + k0 + 8 * c) = o; }
.LBB0_199:
	s_or_b64 exec, exec, s[0:1]
	ds_read2_b32 v[0:1], v19 offset0:16 offset1:49
	s_waitcnt lgkmcnt(0)
	v_mul_f32_e32 v0, v102, v0
	v_mul_f32_e32 v1, v103, v1
	v_cvt_pk_bf16_f32 v0, v0, v1
	ds_read2_b32 v[6:7], v19 offset0:82 offset1:115
	s_waitcnt lgkmcnt(0)
	v_mul_f32_e32 v1, v104, v6
	v_mul_f32_e32 v6, v105, v7
	v_cvt_pk_bf16_f32 v1, v1, v6
	ds_read2_b32 v[6:7], v19 offset0:148 offset1:181
	s_waitcnt lgkmcnt(0)
	v_mul_f32_e32 v2, v106, v6
	v_mul_f32_e32 v3, v107, v7
	v_cvt_pk_bf16_f32 v2, v2, v3
	ds_read2_b32 v[8:9], v19 offset0:214 offset1:247
	v_or_b32_e32 v6, v10, v27
	v_cmp_lt_i32_e64 s[0:1], s43, v6
	s_waitcnt lgkmcnt(0)
	v_mul_f32_e32 v3, v108, v8
	v_mul_f32_e32 v4, v109, v9
	v_cvt_pk_bf16_f32 v3, v3, v4
	s_and_saveexec_b64 s[18:19], s[0:1]
	s_xor_b64 s[18:19], exec, s[18:19]
	s_cbranch_execz .LBB0_233
	v_cmp_lt_u32_e64 s[0:1], s51, v10
	s_and_saveexec_b64 s[20:21], s[0:1]
	s_xor_b64 s[20:21], exec, s[20:21]
	s_cbranch_execz .LBB0_230
	v_cmp_lt_u32_e64 s[0:1], s44, v10
	s_and_saveexec_b64 s[22:23], s[0:1]
	s_xor_b64 s[22:23], exec, s[22:23]
	s_cbranch_execz .LBB0_227
	v_cmp_lt_u32_e64 s[0:1], s56, v10
	s_and_saveexec_b64 s[24:25], s[0:1]
	s_xor_b64 s[24:25], exec, s[24:25]
	s_cbranch_execz .LBB0_224
	v_cmp_lt_u32_e64 s[0:1], s57, v10
	s_and_saveexec_b64 s[26:27], s[0:1]
	s_xor_b64 s[26:27], exec, s[26:27]
	s_cbranch_execz .LBB0_221
	v_cmp_lt_u32_e64 s[0:1], s58, v10
	s_and_saveexec_b64 s[28:29], s[0:1]
	s_xor_b64 s[28:29], exec, s[28:29]
	s_cbranch_execz .LBB0_218
	v_cmp_lt_u32_e64 s[0:1], s59, v10
	s_and_saveexec_b64 s[30:31], s[0:1]
	s_xor_b64 s[30:31], exec, s[30:31]
	s_cbranch_execz .LBB0_215
	v_cmp_lt_u32_e64 s[0:1], s72, v10
	s_and_saveexec_b64 s[34:35], s[0:1]
	s_xor_b64 s[34:35], exec, s[34:35]
	s_cbranch_execz .LBB0_212
	v_cmp_lt_u32_e64 s[0:1], s73, v10
	s_and_saveexec_b64 s[76:77], s[0:1]
	s_xor_b64 s[0:1], exec, s[76:77]
	v_add_u32_e32 v4, 0xfffffc00, v6
	s_andn2_saveexec_b64 s[0:1], s[0:1]
	v_add_u32_e32 v4, 0xfffff400, v6
	s_or_b64 exec, exec, s[0:1]

; #define LAS __attribute__((address_space(3)))
; __device__ __forceinline__ unsigned cvt_pk_bf16(float lo, float hi) { unsigned r; asm volatile("v_cvt_pk_bf16_f32 %0, %1, %2" : "=v"(r) : "v"(lo), "v"(hi)); return r; }
; __device__ __forceinline__ int win_map(int n) {
;     if (n < 1024) { const int d = n & 63; return (n & ~63) + 2 * (d & 31) + (d >> 5); }
;     if (n < 1280) { const int q = n - 1024, d = q & 63; return 2048 + (q & ~63) + 2 * (d & 31) + (d >> 5); }
;     if (n < 1536) return 2304 + (n - 1280);
;     if (n < 2560) return 2560 + (n - 1536);
;     if (n < 3072) return 1024 + (n - 2560);
;     if (n < 3584) { const int ch = n - 3072; return 4608 + 256 * (ch >> 7) + (ch & 127); }
;     if (n < 4096) { const int ch = n - 3584; return 4608 + 256 * (ch >> 7) + 128 + (ch & 127); }
;     if (n < 4608) return 3584 + (n - 4096);
;     if (n < 5120) return 1536 + (n - 4608);
;     return 4096 + (n - 5120);
; }
; template <bool MAPIN>
; __device__ __forceinline__ void transpose_item(const float* W, int K, int N, bf16_t* WT, LAS float* scr, int item, int lane, const float* gk = nullptr) {
;     ...
;     for (int j = 0; j < 4; ++j) { const int n = (lane >> 3) + 8 * j; const LAS float* s = scr + (8 * c) * 33 + n;
;         f32x4 ga = (f32x4){1.f, 1.f, 1.f, 1.f}, gb = ga;
;         if (gk) { ga = *(const f32x4*)(gk + k0 + 8 * c); gb = *(const f32x4*)(gk + k0 + 8 * c + 4); }
;         u32x4 o; o.x = cvt_pk_bf16(s[0 * 33] * ga[0], s[1 * 33] * ga[1]); o.y = cvt_pk_bf16(s[2 * 33] * ga[2], s[3 * 33] * ga[3]); o.z = cvt_pk_bf16(s[4 * 33] * gb[0], s[5 * 33] * gb[1]); o.w = cvt_pk_bf16(s[6 * 33] * gb[2], s[7 * 33] * gb[3]);
;         const int nd = MAPIN ? win_map(n0 + n) : (n0 + n);
;         *(u32x4*)(WT + (size_t)nd * K + k0 + 8 * c) = o; }
.LBB0_237:
	s_or_b64 exec, exec, s[0:1]
	ds_read2_b32 v[0:1], v19 offset0:24 offset1:57
	s_waitcnt lgkmcnt(0)
	v_mul_f32_e32 v0, v102, v0
	v_mul_f32_e32 v1, v103, v1
	v_cvt_pk_bf16_f32 v0, v0, v1
	ds_read2_b32 v[6:7], v19 offset0:90 offset1:123
	s_waitcnt lgkmcnt(0)
	v_mul_f32_e32 v1, v104, v6
	v_mul_f32_e32 v6, v105, v7
	v_cvt_pk_bf16_f32 v1, v1, v6
	ds_read2_b32 v[6:7], v19 offset0:156 offset1:189
	s_waitcnt lgkmcnt(0)
	v_mul_f32_e32 v2, v106, v6
	v_mul_f32_e32 v3, v107, v7
	v_cvt_pk_bf16_f32 v2, v2, v3
	ds_read2_b32 v[8:9], v19 offset0:222 offset1:255
	v_or_b32_e32 v6, v10, v28
	v_cmp_lt_i32_e32 vcc, s43, v6
	s_waitcnt lgkmcnt(0)
	v_mul_f32_e32 v3, v108, v8
	v_mul_f32_e32 v4, v109, v9
	v_cvt_pk_bf16_f32 v3, v3, v4
	s_and_saveexec_b64 s[0:1], vcc
	s_xor_b64 s[0:1], exec, s[0:1]
	s_cbranch_execz .LBB0_271
	v_cmp_lt_u32_e32 vcc, s51, v10
	s_and_saveexec_b64 s[18:19], vcc
	s_xor_b64 s[18:19], exec, s[18:19]
	s_cbranch_execz .LBB0_268
	v_cmp_lt_u32_e32 vcc, s44, v10
	s_and_saveexec_b64 s[20:21], vcc
	s_xor_b64 s[20:21], exec, s[20:21]
	s_cbranch_execz .LBB0_265
	v_cmp_lt_u32_e32 vcc, s56, v10
	s_and_saveexec_b64 s[22:23], vcc
	s_xor_b64 s[22:23], exec, s[22:23]
	s_cbranch_execz .LBB0_262
	v_cmp_lt_u32_e32 vcc, s57, v10
	s_and_saveexec_b64 s[24:25], vcc
	s_xor_b64 s[24:25], exec, s[24:25]
	s_cbranch_execz .LBB0_259
	v_cmp_lt_u32_e32 vcc, s58, v10
	s_and_saveexec_b64 s[26:27], vcc
	s_xor_b64 s[26:27], exec, s[26:27]
	s_cbranch_execz .LBB0_256
	v_cmp_lt_u32_e32 vcc, s59, v10
	s_and_saveexec_b64 s[28:29], vcc
	s_xor_b64 s[28:29], exec, s[28:29]
	s_cbranch_execz .LBB0_253
	v_cmp_lt_u32_e32 vcc, s72, v10
	s_and_saveexec_b64 s[30:31], vcc
	s_xor_b64 s[30:31], exec, s[30:31]
	s_cbranch_execz .LBB0_250
	v_cmp_lt_u32_e32 vcc, s73, v10
	s_and_saveexec_b64 s[34:35], vcc
	s_xor_b64 s[34:35], exec, s[34:35]
	v_add_u32_e32 v4, 0xfffffc00, v6
	s_andn2_saveexec_b64 s[34:35], s[34:35]
	v_add_u32_e32 v4, 0xfffff400, v6
	s_or_b64 exec, exec, s[34:35]
